# P1 SSM Kt pre-pass rewritten: Bbar/C/apow staged once in LDS, two outputs per thread sharing a*B, one global round trip instead of 16 (same f32 arithmetic order)
# speedup vs baseline: 1.0220x; 1.0022x over previous
; #define GAS __attribute__((address_space(1)))
; __device__ __forceinline__ int opq(int v) { asm volatile("" : "+s"(v)); return v; }
; __global__ void __launch_bounds__(512, 2) fwd_mega(Args a) {
;     ...
;         const GAS float* c_re = ((const GAS float*)a.in[opq(I_CRE)]); const GAS float* c_im = ((const GAS float*)a.in[opq(I_CIM)]);
;         for (int idx = gtid; idx < 64 * 16 * 256; idx += NTH) {
;             const int pp = idx & 255, tau = (idx >> 8) & 15, dg = idx >> 12, p = pp >> 4, p2 = pp & 15;
;             float acc = 0.f;
; #pragma unroll 8
;             for (int n = 0; n < 64; ++n) {
;                 const float wr_ = apow[((size_t)(dg * 17 + tau) * 64 + n) * 2], wi_ = apow[((size_t)(dg * 17 + tau) * 64 + n) * 2 + 1];
;                 const float br = Bbar[(((size_t)dg * 64 + n) * 16 + p2) * 2], bi = Bbar[(((size_t)dg * 64 + n) * 16 + p2) * 2 + 1];
;                 const float xr = wr_ * br - wi_ * bi, xi = wr_ * bi + wi_ * br;
;                 acc += c_re[((size_t)dg * 16 + p) * 64 + n] * xr - c_im[((size_t)dg * 16 + p) * 64 + n] * xi;
;             }
;             Kt[idx] = acc;
;         }
.LBB0_161:
	s_or_b64 exec, exec, s[4:5]
	s_mov_b64 s[30:31], s[14:15]
	s_mov_b64 s[34:35], s[12:13]
	v_mov_b32_e32 v1, v184
	s_waitcnt lgkmcnt(0)
	s_barrier
	s_mov_b32 s5, 0x40000
	v_add_u32_e32 v14, s3, v1
	s_mov_b32 s8, 11
	s_mov_b32 s4, 12
	v_cmp_gt_i32_e32 vcc, s5, v14
	s_and_saveexec_b64 s[6:7], vcc
	s_cbranch_execz .LBB0_170
	s_ashr_i32 s9, s8, 31
	s_lshl_b64 s[8:9], s[8:9], 3
	s_add_u32 s10, s0, s8
	s_addc_u32 s11, s1, s9
	s_ashr_i32 s5, s4, 31
	s_lshl_b64 s[4:5], s[4:5], 3
	s_add_u32 s4, s0, s4
	s_addc_u32 s5, s1, s5
	s_load_dwordx2 s[8:9], s[10:11], 0x0
	s_load_dwordx2 s[36:37], s[4:5], 0x0
	s_add_u32 s38, s30, 0x2700000
	s_addc_u32 s39, s31, 0
	s_lshr_b32 s4, s3, 11
	s_bfe_u32 s5, s3, 0x20009
	v_add_u32_e32 v0, s79, v1
	v_lshlrev_b32_e32 v2, 4, v0
	s_lshl_b32 s10, s4, 13
	s_add_u32 s40, s30, 0x2600000
	s_addc_u32 s41, s31, 0
	s_add_u32 s40, s40, s10
	s_addc_u32 s41, s41, 0
	global_load_dwordx4 v[16:19], v2, s[40:41]
	s_lshl_b32 s10, s4, 12
	s_waitcnt lgkmcnt(0)
	s_cmpk_lt_u32 s79, 0x100
	s_cselect_b32 s42, s8, s36
	s_cselect_b32 s43, s9, s37
	s_add_u32 s42, s42, s10
	s_addc_u32 s43, s43, 0
	v_and_b32_e32 v3, 0xff, v0
	v_lshlrev_b32_e32 v4, 4, v3
	global_load_dwordx4 v[20:23], v4, s[42:43]
	s_mul_i32 s10, s4, 17
	s_lshl_b32 s11, s5, 2
	s_add_i32 s10, s10, s11
	s_lshl_b32 s10, s10, 9
	s_add_u32 s44, s30, 0x2500000
	s_addc_u32 s45, s31, 0
	s_add_u32 s44, s44, s10
	s_addc_u32 s45, s45, 0
	s_cmpk_lt_u32 s79, 0x80
	s_cbranch_scc0 .Lkt_noa
	global_load_dwordx4 v[24:27], v2, s[44:45]
.Lkt_noa:
	v_and_b32_e32 v5, 7, v0
	v_mul_u32_u24_e32 v5, 0x420, v5
	v_lshrrev_b32_e32 v6, 3, v0
	v_lshl_add_u32 v5, v6, 3, v5
	v_lshrrev_b32_e32 v6, 4, v3
	v_mul_u32_u24_e32 v6, 0x210, v6
	v_and_b32_e32 v8, 15, v0
	v_lshl_add_u32 v6, v8, 5, v6
	v_lshrrev_b32_e32 v8, 8, v0
	v_lshl_add_u32 v6, v8, 2, v6
	v_add_u32_e32 v7, 0x2100, v6
	v_add_u32_e32 v9, 0x4200, v2
	s_lshr_b32 s11, s79, 7
	s_lshl_b32 s11, s11, 9
	s_add_i32 s11, s11, 0x4200
	v_mov_b32_e32 v149, s11
	v_and_b32_e32 v150, 15, v1
	v_mul_u32_u24_e32 v150, 0x210, v150
	v_bfe_u32 v151, v0, 4, 3
	v_mul_u32_u24_e32 v151, 0x210, v151
	v_add_u32_e32 v151, 0x2100, v151
	v_mov_b32_e32 v15, 0
	v_mov_b32_e32 v148, 0
	s_waitcnt vmcnt(0)
	ds_write_b64 v5, v[16:17]
	ds_write_b64 v5, v[18:19] offset:528
	ds_write2_b32 v7, v20, v21 offset1:2
	ds_write2_b32 v7, v22, v23 offset0:4 offset1:6
	s_cmpk_lt_u32 s79, 0x80
	s_cbranch_scc0 .Lkt_noa2
	ds_write_b128 v9, v[24:27]
.Lkt_noa2:
	s_waitcnt lgkmcnt(0)
	s_barrier
	ds_read_b128 v[16:19], v149 offset:0
	ds_read_b128 v[20:23], v150 offset:0
	ds_read_b128 v[24:27], v151 offset:0
	ds_read_b128 v[28:31], v151 offset:4224
	ds_read_b128 v[32:35], v149 offset:16
	ds_read_b128 v[36:39], v150 offset:16
	ds_read_b128 v[40:43], v151 offset:16
	ds_read_b128 v[44:47], v151 offset:4240
	ds_read_b128 v[48:51], v149 offset:32
	ds_read_b128 v[52:55], v150 offset:32
	ds_read_b128 v[56:59], v151 offset:32
	ds_read_b128 v[60:63], v151 offset:4256
	s_waitcnt lgkmcnt(8)
	v_pk_mul_f32 v[2:3], v[16:17], v[20:21] op_sel:[1,1] op_sel_hi:[0,1]
	v_pk_mul_f32 v[4:5], v[18:19], v[22:23] op_sel:[1,1] op_sel_hi:[0,1]
	v_pk_fma_f32 v[6:7], v[16:17], v[20:21], v[2:3] op_sel_hi:[1,0,1] neg_lo:[0,0,1]
	v_pk_fma_f32 v[8:9], v[18:19], v[22:23], v[4:5] op_sel_hi:[1,0,1] neg_lo:[0,0,1]
	v_pk_mul_f32 v[10:11], v[24:25], v[6:7]
	v_pk_mul_f32 v[12:13], v[28:29], v[6:7]
	v_pk_mul_f32 v[144:145], v[26:27], v[8:9]
	v_pk_mul_f32 v[146:147], v[30:31], v[8:9]
	v_sub_f32_e32 v10, v10, v11
	v_sub_f32_e32 v12, v12, v13
	v_sub_f32_e32 v144, v144, v145
	v_sub_f32_e32 v146, v146, v147
	v_add_f32_e32 v15, v15, v10
	v_add_f32_e32 v148, v148, v12
	v_add_f32_e32 v15, v15, v144
	v_add_f32_e32 v148, v148, v146
	ds_read_b128 v[16:19], v149 offset:48
	ds_read_b128 v[20:23], v150 offset:48
	ds_read_b128 v[24:27], v151 offset:48
	ds_read_b128 v[28:31], v151 offset:4272
	s_waitcnt lgkmcnt(8)
	v_pk_mul_f32 v[2:3], v[32:33], v[36:37] op_sel:[1,1] op_sel_hi:[0,1]
	v_pk_mul_f32 v[4:5], v[34:35], v[38:39] op_sel:[1,1] op_sel_hi:[0,1]
	v_pk_fma_f32 v[6:7], v[32:33], v[36:37], v[2:3] op_sel_hi:[1,0,1] neg_lo:[0,0,1]
	v_pk_fma_f32 v[8:9], v[34:35], v[38:39], v[4:5] op_sel_hi:[1,0,1] neg_lo:[0,0,1]
	v_pk_mul_f32 v[10:11], v[40:41], v[6:7]
	v_pk_mul_f32 v[12:13], v[44:45], v[6:7]
	v_pk_mul_f32 v[144:145], v[42:43], v[8:9]
	v_pk_mul_f32 v[146:147], v[46:47], v[8:9]
	v_sub_f32_e32 v10, v10, v11
	v_sub_f32_e32 v12, v12, v13
	v_sub_f32_e32 v144, v144, v145
	v_sub_f32_e32 v146, v146, v147
	v_add_f32_e32 v15, v15, v10
	v_add_f32_e32 v148, v148, v12
	v_add_f32_e32 v15, v15, v144
	v_add_f32_e32 v148, v148, v146
	ds_read_b128 v[32:35], v149 offset:64
	ds_read_b128 v[36:39], v150 offset:64
	ds_read_b128 v[40:43], v151 offset:64
	ds_read_b128 v[44:47], v151 offset:4288
	s_waitcnt lgkmcnt(8)
	v_pk_mul_f32 v[2:3], v[48:49], v[52:53] op_sel:[1,1] op_sel_hi:[0,1]
	v_pk_mul_f32 v[4:5], v[50:51], v[54:55] op_sel:[1,1] op_sel_hi:[0,1]
	v_pk_fma_f32 v[6:7], v[48:49], v[52:53], v[2:3] op_sel_hi:[1,0,1] neg_lo:[0,0,1]
	v_pk_fma_f32 v[8:9], v[50:51], v[54:55], v[4:5] op_sel_hi:[1,0,1] neg_lo:[0,0,1]
	v_pk_mul_f32 v[10:11], v[56:57], v[6:7]
	v_pk_mul_f32 v[12:13], v[60:61], v[6:7]
	v_pk_mul_f32 v[144:145], v[58:59], v[8:9]
	v_pk_mul_f32 v[146:147], v[62:63], v[8:9]
	v_sub_f32_e32 v10, v10, v11
	v_sub_f32_e32 v12, v12, v13
	v_sub_f32_e32 v144, v144, v145
	v_sub_f32_e32 v146, v146, v147
	v_add_f32_e32 v15, v15, v10
	v_add_f32_e32 v148, v148, v12
	v_add_f32_e32 v15, v15, v144
	v_add_f32_e32 v148, v148, v146
	ds_read_b128 v[48:51], v149 offset:80
	ds_read_b128 v[52:55], v150 offset:80
	ds_read_b128 v[56:59], v151 offset:80
	ds_read_b128 v[60:63], v151 offset:4304
	s_waitcnt lgkmcnt(8)
; __global__ void __launch_bounds__(512, 2) fwd_mega(Args a) {
;     ...
;             for (int n = 0; n < 64; ++n) {
;                 const float wr_ = apow[((size_t)(dg * 17 + tau) * 64 + n) * 2], wi_ = apow[((size_t)(dg * 17 + tau) * 64 + n) * 2 + 1];
;                 const float br = Bbar[(((size_t)dg * 64 + n) * 16 + p2) * 2], bi = Bbar[(((size_t)dg * 64 + n) * 16 + p2) * 2 + 1];
;                 const float xr = wr_ * br - wi_ * bi, xi = wr_ * bi + wi_ * br;
;                 acc += c_re[((size_t)dg * 16 + p) * 64 + n] * xr - c_im[((size_t)dg * 16 + p) * 64 + n] * xi;
;             }
	v_pk_mul_f32 v[2:3], v[16:17], v[20:21] op_sel:[1,1] op_sel_hi:[0,1]
	v_pk_mul_f32 v[4:5], v[18:19], v[22:23] op_sel:[1,1] op_sel_hi:[0,1]
	v_pk_fma_f32 v[6:7], v[16:17], v[20:21], v[2:3] op_sel_hi:[1,0,1] neg_lo:[0,0,1]
	v_pk_fma_f32 v[8:9], v[18:19], v[22:23], v[4:5] op_sel_hi:[1,0,1] neg_lo:[0,0,1]
	v_pk_mul_f32 v[10:11], v[24:25], v[6:7]
	v_pk_mul_f32 v[12:13], v[28:29], v[6:7]
	v_pk_mul_f32 v[144:145], v[26:27], v[8:9]
	v_pk_mul_f32 v[146:147], v[30:31], v[8:9]
	v_sub_f32_e32 v10, v10, v11
	v_sub_f32_e32 v12, v12, v13
	v_sub_f32_e32 v144, v144, v145
	v_sub_f32_e32 v146, v146, v147
	v_add_f32_e32 v15, v15, v10
	v_add_f32_e32 v148, v148, v12
	v_add_f32_e32 v15, v15, v144
	v_add_f32_e32 v148, v148, v146
	ds_read_b128 v[16:19], v149 offset:96
	ds_read_b128 v[20:23], v150 offset:96
	ds_read_b128 v[24:27], v151 offset:96
	ds_read_b128 v[28:31], v151 offset:4320
	s_waitcnt lgkmcnt(8)
	v_pk_mul_f32 v[2:3], v[32:33], v[36:37] op_sel:[1,1] op_sel_hi:[0,1]
	v_pk_mul_f32 v[4:5], v[34:35], v[38:39] op_sel:[1,1] op_sel_hi:[0,1]
	v_pk_fma_f32 v[6:7], v[32:33], v[36:37], v[2:3] op_sel_hi:[1,0,1] neg_lo:[0,0,1]
	v_pk_fma_f32 v[8:9], v[34:35], v[38:39], v[4:5] op_sel_hi:[1,0,1] neg_lo:[0,0,1]
	v_pk_mul_f32 v[10:11], v[40:41], v[6:7]
	v_pk_mul_f32 v[12:13], v[44:45], v[6:7]
	v_pk_mul_f32 v[144:145], v[42:43], v[8:9]
	v_pk_mul_f32 v[146:147], v[46:47], v[8:9]
	v_sub_f32_e32 v10, v10, v11
	v_sub_f32_e32 v12, v12, v13
	v_sub_f32_e32 v144, v144, v145
	v_sub_f32_e32 v146, v146, v147
	v_add_f32_e32 v15, v15, v10
	v_add_f32_e32 v148, v148, v12
	v_add_f32_e32 v15, v15, v144
	v_add_f32_e32 v148, v148, v146
	ds_read_b128 v[32:35], v149 offset:112
	ds_read_b128 v[36:39], v150 offset:112
	ds_read_b128 v[40:43], v151 offset:112
	ds_read_b128 v[44:47], v151 offset:4336
	s_waitcnt lgkmcnt(8)
	v_pk_mul_f32 v[2:3], v[48:49], v[52:53] op_sel:[1,1] op_sel_hi:[0,1]
	v_pk_mul_f32 v[4:5], v[50:51], v[54:55] op_sel:[1,1] op_sel_hi:[0,1]
	v_pk_fma_f32 v[6:7], v[48:49], v[52:53], v[2:3] op_sel_hi:[1,0,1] neg_lo:[0,0,1]
	v_pk_fma_f32 v[8:9], v[50:51], v[54:55], v[4:5] op_sel_hi:[1,0,1] neg_lo:[0,0,1]
	v_pk_mul_f32 v[10:11], v[56:57], v[6:7]
	v_pk_mul_f32 v[12:13], v[60:61], v[6:7]
	v_pk_mul_f32 v[144:145], v[58:59], v[8:9]
	v_pk_mul_f32 v[146:147], v[62:63], v[8:9]
	v_sub_f32_e32 v10, v10, v11
	v_sub_f32_e32 v12, v12, v13
	v_sub_f32_e32 v144, v144, v145
	v_sub_f32_e32 v146, v146, v147
	v_add_f32_e32 v15, v15, v10
	v_add_f32_e32 v148, v148, v12
	v_add_f32_e32 v15, v15, v144
	v_add_f32_e32 v148, v148, v146
	ds_read_b128 v[48:51], v149 offset:128
	ds_read_b128 v[52:55], v150 offset:128
	ds_read_b128 v[56:59], v151 offset:128
	ds_read_b128 v[60:63], v151 offset:4352
	s_waitcnt lgkmcnt(8)
	v_pk_mul_f32 v[2:3], v[16:17], v[20:21] op_sel:[1,1] op_sel_hi:[0,1]
	v_pk_mul_f32 v[4:5], v[18:19], v[22:23] op_sel:[1,1] op_sel_hi:[0,1]
	v_pk_fma_f32 v[6:7], v[16:17], v[20:21], v[2:3] op_sel_hi:[1,0,1] neg_lo:[0,0,1]
	v_pk_fma_f32 v[8:9], v[18:19], v[22:23], v[4:5] op_sel_hi:[1,0,1] neg_lo:[0,0,1]
	v_pk_mul_f32 v[10:11], v[24:25], v[6:7]
	v_pk_mul_f32 v[12:13], v[28:29], v[6:7]
	v_pk_mul_f32 v[144:145], v[26:27], v[8:9]
	v_pk_mul_f32 v[146:147], v[30:31], v[8:9]
	v_sub_f32_e32 v10, v10, v11
	v_sub_f32_e32 v12, v12, v13
	v_sub_f32_e32 v144, v144, v145
	v_sub_f32_e32 v146, v146, v147
	v_add_f32_e32 v15, v15, v10
	v_add_f32_e32 v148, v148, v12
	v_add_f32_e32 v15, v15, v144
	v_add_f32_e32 v148, v148, v146
	ds_read_b128 v[16:19], v149 offset:144
	ds_read_b128 v[20:23], v150 offset:144
	ds_read_b128 v[24:27], v151 offset:144
	ds_read_b128 v[28:31], v151 offset:4368
	s_waitcnt lgkmcnt(8)
	v_pk_mul_f32 v[2:3], v[32:33], v[36:37] op_sel:[1,1] op_sel_hi:[0,1]
	v_pk_mul_f32 v[4:5], v[34:35], v[38:39] op_sel:[1,1] op_sel_hi:[0,1]
	v_pk_fma_f32 v[6:7], v[32:33], v[36:37], v[2:3] op_sel_hi:[1,0,1] neg_lo:[0,0,1]
	v_pk_fma_f32 v[8:9], v[34:35], v[38:39], v[4:5] op_sel_hi:[1,0,1] neg_lo:[0,0,1]
	v_pk_mul_f32 v[10:11], v[40:41], v[6:7]
	v_pk_mul_f32 v[12:13], v[44:45], v[6:7]
	v_pk_mul_f32 v[144:145], v[42:43], v[8:9]
	v_pk_mul_f32 v[146:147], v[46:47], v[8:9]
	v_sub_f32_e32 v10, v10, v11
	v_sub_f32_e32 v12, v12, v13
	v_sub_f32_e32 v144, v144, v145
	v_sub_f32_e32 v146, v146, v147
	v_add_f32_e32 v15, v15, v10
	v_add_f32_e32 v148, v148, v12
	v_add_f32_e32 v15, v15, v144
	v_add_f32_e32 v148, v148, v146
	ds_read_b128 v[32:35], v149 offset:160
	ds_read_b128 v[36:39], v150 offset:160
	ds_read_b128 v[40:43], v151 offset:160
	ds_read_b128 v[44:47], v151 offset:4384
	s_waitcnt lgkmcnt(8)
	v_pk_mul_f32 v[2:3], v[48:49], v[52:53] op_sel:[1,1] op_sel_hi:[0,1]
	v_pk_mul_f32 v[4:5], v[50:51], v[54:55] op_sel:[1,1] op_sel_hi:[0,1]
	v_pk_fma_f32 v[6:7], v[48:49], v[52:53], v[2:3] op_sel_hi:[1,0,1] neg_lo:[0,0,1]
	v_pk_fma_f32 v[8:9], v[50:51], v[54:55], v[4:5] op_sel_hi:[1,0,1] neg_lo:[0,0,1]
	v_pk_mul_f32 v[10:11], v[56:57], v[6:7]
	v_pk_mul_f32 v[12:13], v[60:61], v[6:7]
	v_pk_mul_f32 v[144:145], v[58:59], v[8:9]
	v_pk_mul_f32 v[146:147], v[62:63], v[8:9]
	v_sub_f32_e32 v10, v10, v11
	v_sub_f32_e32 v12, v12, v13
	v_sub_f32_e32 v144, v144, v145
	v_sub_f32_e32 v146, v146, v147
	v_add_f32_e32 v15, v15, v10
	v_add_f32_e32 v148, v148, v12
	v_add_f32_e32 v15, v15, v144
	v_add_f32_e32 v148, v148, v146
	ds_read_b128 v[48:51], v149 offset:176
	ds_read_b128 v[52:55], v150 offset:176
	ds_read_b128 v[56:59], v151 offset:176
	ds_read_b128 v[60:63], v151 offset:4400
	s_waitcnt lgkmcnt(8)
; __global__ void __launch_bounds__(512, 2) fwd_mega(Args a) {
;     ...
;             for (int n = 0; n < 64; ++n) {
;                 const float wr_ = apow[((size_t)(dg * 17 + tau) * 64 + n) * 2], wi_ = apow[((size_t)(dg * 17 + tau) * 64 + n) * 2 + 1];
;                 const float br = Bbar[(((size_t)dg * 64 + n) * 16 + p2) * 2], bi = Bbar[(((size_t)dg * 64 + n) * 16 + p2) * 2 + 1];
;                 const float xr = wr_ * br - wi_ * bi, xi = wr_ * bi + wi_ * br;
;                 acc += c_re[((size_t)dg * 16 + p) * 64 + n] * xr - c_im[((size_t)dg * 16 + p) * 64 + n] * xi;
;             }
	v_pk_mul_f32 v[2:3], v[16:17], v[20:21] op_sel:[1,1] op_sel_hi:[0,1]
	v_pk_mul_f32 v[4:5], v[18:19], v[22:23] op_sel:[1,1] op_sel_hi:[0,1]
	v_pk_fma_f32 v[6:7], v[16:17], v[20:21], v[2:3] op_sel_hi:[1,0,1] neg_lo:[0,0,1]
	v_pk_fma_f32 v[8:9], v[18:19], v[22:23], v[4:5] op_sel_hi:[1,0,1] neg_lo:[0,0,1]
	v_pk_mul_f32 v[10:11], v[24:25], v[6:7]
	v_pk_mul_f32 v[12:13], v[28:29], v[6:7]
	v_pk_mul_f32 v[144:145], v[26:27], v[8:9]
	v_pk_mul_f32 v[146:147], v[30:31], v[8:9]
	v_sub_f32_e32 v10, v10, v11
	v_sub_f32_e32 v12, v12, v13
	v_sub_f32_e32 v144, v144, v145
	v_sub_f32_e32 v146, v146, v147
	v_add_f32_e32 v15, v15, v10
	v_add_f32_e32 v148, v148, v12
	v_add_f32_e32 v15, v15, v144
	v_add_f32_e32 v148, v148, v146
	ds_read_b128 v[16:19], v149 offset:192
	ds_read_b128 v[20:23], v150 offset:192
	ds_read_b128 v[24:27], v151 offset:192
	ds_read_b128 v[28:31], v151 offset:4416
	s_waitcnt lgkmcnt(8)
	v_pk_mul_f32 v[2:3], v[32:33], v[36:37] op_sel:[1,1] op_sel_hi:[0,1]
	v_pk_mul_f32 v[4:5], v[34:35], v[38:39] op_sel:[1,1] op_sel_hi:[0,1]
	v_pk_fma_f32 v[6:7], v[32:33], v[36:37], v[2:3] op_sel_hi:[1,0,1] neg_lo:[0,0,1]
	v_pk_fma_f32 v[8:9], v[34:35], v[38:39], v[4:5] op_sel_hi:[1,0,1] neg_lo:[0,0,1]
	v_pk_mul_f32 v[10:11], v[40:41], v[6:7]
	v_pk_mul_f32 v[12:13], v[44:45], v[6:7]
	v_pk_mul_f32 v[144:145], v[42:43], v[8:9]
	v_pk_mul_f32 v[146:147], v[46:47], v[8:9]
	v_sub_f32_e32 v10, v10, v11
	v_sub_f32_e32 v12, v12, v13
	v_sub_f32_e32 v144, v144, v145
	v_sub_f32_e32 v146, v146, v147
	v_add_f32_e32 v15, v15, v10
	v_add_f32_e32 v148, v148, v12
	v_add_f32_e32 v15, v15, v144
	v_add_f32_e32 v148, v148, v146
	ds_read_b128 v[32:35], v149 offset:208
	ds_read_b128 v[36:39], v150 offset:208
	ds_read_b128 v[40:43], v151 offset:208
	ds_read_b128 v[44:47], v151 offset:4432
	s_waitcnt lgkmcnt(8)
	v_pk_mul_f32 v[2:3], v[48:49], v[52:53] op_sel:[1,1] op_sel_hi:[0,1]
	v_pk_mul_f32 v[4:5], v[50:51], v[54:55] op_sel:[1,1] op_sel_hi:[0,1]
	v_pk_fma_f32 v[6:7], v[48:49], v[52:53], v[2:3] op_sel_hi:[1,0,1] neg_lo:[0,0,1]
	v_pk_fma_f32 v[8:9], v[50:51], v[54:55], v[4:5] op_sel_hi:[1,0,1] neg_lo:[0,0,1]
	v_pk_mul_f32 v[10:11], v[56:57], v[6:7]
	v_pk_mul_f32 v[12:13], v[60:61], v[6:7]
	v_pk_mul_f32 v[144:145], v[58:59], v[8:9]
	v_pk_mul_f32 v[146:147], v[62:63], v[8:9]
	v_sub_f32_e32 v10, v10, v11
	v_sub_f32_e32 v12, v12, v13
	v_sub_f32_e32 v144, v144, v145
	v_sub_f32_e32 v146, v146, v147
	v_add_f32_e32 v15, v15, v10
	v_add_f32_e32 v148, v148, v12
	v_add_f32_e32 v15, v15, v144
	v_add_f32_e32 v148, v148, v146
	ds_read_b128 v[48:51], v149 offset:224
	ds_read_b128 v[52:55], v150 offset:224
	ds_read_b128 v[56:59], v151 offset:224
	ds_read_b128 v[60:63], v151 offset:4448
	s_waitcnt lgkmcnt(8)
	v_pk_mul_f32 v[2:3], v[16:17], v[20:21] op_sel:[1,1] op_sel_hi:[0,1]
	v_pk_mul_f32 v[4:5], v[18:19], v[22:23] op_sel:[1,1] op_sel_hi:[0,1]
	v_pk_fma_f32 v[6:7], v[16:17], v[20:21], v[2:3] op_sel_hi:[1,0,1] neg_lo:[0,0,1]
	v_pk_fma_f32 v[8:9], v[18:19], v[22:23], v[4:5] op_sel_hi:[1,0,1] neg_lo:[0,0,1]
	v_pk_mul_f32 v[10:11], v[24:25], v[6:7]
	v_pk_mul_f32 v[12:13], v[28:29], v[6:7]
	v_pk_mul_f32 v[144:145], v[26:27], v[8:9]
	v_pk_mul_f32 v[146:147], v[30:31], v[8:9]
	v_sub_f32_e32 v10, v10, v11
	v_sub_f32_e32 v12, v12, v13
	v_sub_f32_e32 v144, v144, v145
	v_sub_f32_e32 v146, v146, v147
	v_add_f32_e32 v15, v15, v10
	v_add_f32_e32 v148, v148, v12
	v_add_f32_e32 v15, v15, v144
	v_add_f32_e32 v148, v148, v146
	ds_read_b128 v[16:19], v149 offset:240
	ds_read_b128 v[20:23], v150 offset:240
	ds_read_b128 v[24:27], v151 offset:240
	ds_read_b128 v[28:31], v151 offset:4464
	s_waitcnt lgkmcnt(8)
	v_pk_mul_f32 v[2:3], v[32:33], v[36:37] op_sel:[1,1] op_sel_hi:[0,1]
	v_pk_mul_f32 v[4:5], v[34:35], v[38:39] op_sel:[1,1] op_sel_hi:[0,1]
	v_pk_fma_f32 v[6:7], v[32:33], v[36:37], v[2:3] op_sel_hi:[1,0,1] neg_lo:[0,0,1]
	v_pk_fma_f32 v[8:9], v[34:35], v[38:39], v[4:5] op_sel_hi:[1,0,1] neg_lo:[0,0,1]
	v_pk_mul_f32 v[10:11], v[40:41], v[6:7]
	v_pk_mul_f32 v[12:13], v[44:45], v[6:7]
	v_pk_mul_f32 v[144:145], v[42:43], v[8:9]
	v_pk_mul_f32 v[146:147], v[46:47], v[8:9]
	v_sub_f32_e32 v10, v10, v11
	v_sub_f32_e32 v12, v12, v13
	v_sub_f32_e32 v144, v144, v145
	v_sub_f32_e32 v146, v146, v147
	v_add_f32_e32 v15, v15, v10
	v_add_f32_e32 v148, v148, v12
	v_add_f32_e32 v15, v15, v144
	v_add_f32_e32 v148, v148, v146
	ds_read_b128 v[32:35], v149 offset:256
	ds_read_b128 v[36:39], v150 offset:256
	ds_read_b128 v[40:43], v151 offset:256
	ds_read_b128 v[44:47], v151 offset:4480
	s_waitcnt lgkmcnt(8)
	v_pk_mul_f32 v[2:3], v[48:49], v[52:53] op_sel:[1,1] op_sel_hi:[0,1]
	v_pk_mul_f32 v[4:5], v[50:51], v[54:55] op_sel:[1,1] op_sel_hi:[0,1]
	v_pk_fma_f32 v[6:7], v[48:49], v[52:53], v[2:3] op_sel_hi:[1,0,1] neg_lo:[0,0,1]
	v_pk_fma_f32 v[8:9], v[50:51], v[54:55], v[4:5] op_sel_hi:[1,0,1] neg_lo:[0,0,1]
	v_pk_mul_f32 v[10:11], v[56:57], v[6:7]
	v_pk_mul_f32 v[12:13], v[60:61], v[6:7]
	v_pk_mul_f32 v[144:145], v[58:59], v[8:9]
	v_pk_mul_f32 v[146:147], v[62:63], v[8:9]
	v_sub_f32_e32 v10, v10, v11
	v_sub_f32_e32 v12, v12, v13
	v_sub_f32_e32 v144, v144, v145
	v_sub_f32_e32 v146, v146, v147
	v_add_f32_e32 v15, v15, v10
	v_add_f32_e32 v148, v148, v12
	v_add_f32_e32 v15, v15, v144
	v_add_f32_e32 v148, v148, v146
	ds_read_b128 v[48:51], v149 offset:272
	ds_read_b128 v[52:55], v150 offset:272
	ds_read_b128 v[56:59], v151 offset:272
	ds_read_b128 v[60:63], v151 offset:4496
	s_waitcnt lgkmcnt(8)
; __global__ void __launch_bounds__(512, 2) fwd_mega(Args a) {
;     ...
;             for (int n = 0; n < 64; ++n) {
;                 const float wr_ = apow[((size_t)(dg * 17 + tau) * 64 + n) * 2], wi_ = apow[((size_t)(dg * 17 + tau) * 64 + n) * 2 + 1];
;                 const float br = Bbar[(((size_t)dg * 64 + n) * 16 + p2) * 2], bi = Bbar[(((size_t)dg * 64 + n) * 16 + p2) * 2 + 1];
;                 const float xr = wr_ * br - wi_ * bi, xi = wr_ * bi + wi_ * br;
;                 acc += c_re[((size_t)dg * 16 + p) * 64 + n] * xr - c_im[((size_t)dg * 16 + p) * 64 + n] * xi;
;             }
	v_pk_mul_f32 v[2:3], v[16:17], v[20:21] op_sel:[1,1] op_sel_hi:[0,1]
	v_pk_mul_f32 v[4:5], v[18:19], v[22:23] op_sel:[1,1] op_sel_hi:[0,1]
	v_pk_fma_f32 v[6:7], v[16:17], v[20:21], v[2:3] op_sel_hi:[1,0,1] neg_lo:[0,0,1]
	v_pk_fma_f32 v[8:9], v[18:19], v[22:23], v[4:5] op_sel_hi:[1,0,1] neg_lo:[0,0,1]
	v_pk_mul_f32 v[10:11], v[24:25], v[6:7]
	v_pk_mul_f32 v[12:13], v[28:29], v[6:7]
	v_pk_mul_f32 v[144:145], v[26:27], v[8:9]
	v_pk_mul_f32 v[146:147], v[30:31], v[8:9]
	v_sub_f32_e32 v10, v10, v11
	v_sub_f32_e32 v12, v12, v13
	v_sub_f32_e32 v144, v144, v145
	v_sub_f32_e32 v146, v146, v147
	v_add_f32_e32 v15, v15, v10
	v_add_f32_e32 v148, v148, v12
	v_add_f32_e32 v15, v15, v144
	v_add_f32_e32 v148, v148, v146
	ds_read_b128 v[16:19], v149 offset:288
	ds_read_b128 v[20:23], v150 offset:288
	ds_read_b128 v[24:27], v151 offset:288
	ds_read_b128 v[28:31], v151 offset:4512
	s_waitcnt lgkmcnt(8)
	v_pk_mul_f32 v[2:3], v[32:33], v[36:37] op_sel:[1,1] op_sel_hi:[0,1]
	v_pk_mul_f32 v[4:5], v[34:35], v[38:39] op_sel:[1,1] op_sel_hi:[0,1]
	v_pk_fma_f32 v[6:7], v[32:33], v[36:37], v[2:3] op_sel_hi:[1,0,1] neg_lo:[0,0,1]
	v_pk_fma_f32 v[8:9], v[34:35], v[38:39], v[4:5] op_sel_hi:[1,0,1] neg_lo:[0,0,1]
	v_pk_mul_f32 v[10:11], v[40:41], v[6:7]
	v_pk_mul_f32 v[12:13], v[44:45], v[6:7]
	v_pk_mul_f32 v[144:145], v[42:43], v[8:9]
	v_pk_mul_f32 v[146:147], v[46:47], v[8:9]
	v_sub_f32_e32 v10, v10, v11
	v_sub_f32_e32 v12, v12, v13
	v_sub_f32_e32 v144, v144, v145
	v_sub_f32_e32 v146, v146, v147
	v_add_f32_e32 v15, v15, v10
	v_add_f32_e32 v148, v148, v12
	v_add_f32_e32 v15, v15, v144
	v_add_f32_e32 v148, v148, v146
	ds_read_b128 v[32:35], v149 offset:304
	ds_read_b128 v[36:39], v150 offset:304
	ds_read_b128 v[40:43], v151 offset:304
	ds_read_b128 v[44:47], v151 offset:4528
	s_waitcnt lgkmcnt(8)
	v_pk_mul_f32 v[2:3], v[48:49], v[52:53] op_sel:[1,1] op_sel_hi:[0,1]
	v_pk_mul_f32 v[4:5], v[50:51], v[54:55] op_sel:[1,1] op_sel_hi:[0,1]
	v_pk_fma_f32 v[6:7], v[48:49], v[52:53], v[2:3] op_sel_hi:[1,0,1] neg_lo:[0,0,1]
	v_pk_fma_f32 v[8:9], v[50:51], v[54:55], v[4:5] op_sel_hi:[1,0,1] neg_lo:[0,0,1]
	v_pk_mul_f32 v[10:11], v[56:57], v[6:7]
	v_pk_mul_f32 v[12:13], v[60:61], v[6:7]
	v_pk_mul_f32 v[144:145], v[58:59], v[8:9]
	v_pk_mul_f32 v[146:147], v[62:63], v[8:9]
	v_sub_f32_e32 v10, v10, v11
	v_sub_f32_e32 v12, v12, v13
	v_sub_f32_e32 v144, v144, v145
	v_sub_f32_e32 v146, v146, v147
	v_add_f32_e32 v15, v15, v10
	v_add_f32_e32 v148, v148, v12
	v_add_f32_e32 v15, v15, v144
	v_add_f32_e32 v148, v148, v146
	ds_read_b128 v[48:51], v149 offset:320
	ds_read_b128 v[52:55], v150 offset:320
	ds_read_b128 v[56:59], v151 offset:320
	ds_read_b128 v[60:63], v151 offset:4544
	s_waitcnt lgkmcnt(8)
	v_pk_mul_f32 v[2:3], v[16:17], v[20:21] op_sel:[1,1] op_sel_hi:[0,1]
	v_pk_mul_f32 v[4:5], v[18:19], v[22:23] op_sel:[1,1] op_sel_hi:[0,1]
	v_pk_fma_f32 v[6:7], v[16:17], v[20:21], v[2:3] op_sel_hi:[1,0,1] neg_lo:[0,0,1]
	v_pk_fma_f32 v[8:9], v[18:19], v[22:23], v[4:5] op_sel_hi:[1,0,1] neg_lo:[0,0,1]
	v_pk_mul_f32 v[10:11], v[24:25], v[6:7]
	v_pk_mul_f32 v[12:13], v[28:29], v[6:7]
	v_pk_mul_f32 v[144:145], v[26:27], v[8:9]
	v_pk_mul_f32 v[146:147], v[30:31], v[8:9]
	v_sub_f32_e32 v10, v10, v11
	v_sub_f32_e32 v12, v12, v13
	v_sub_f32_e32 v144, v144, v145
	v_sub_f32_e32 v146, v146, v147
	v_add_f32_e32 v15, v15, v10
	v_add_f32_e32 v148, v148, v12
	v_add_f32_e32 v15, v15, v144
	v_add_f32_e32 v148, v148, v146
	ds_read_b128 v[16:19], v149 offset:336
	ds_read_b128 v[20:23], v150 offset:336
	ds_read_b128 v[24:27], v151 offset:336
	ds_read_b128 v[28:31], v151 offset:4560
	s_waitcnt lgkmcnt(8)
	v_pk_mul_f32 v[2:3], v[32:33], v[36:37] op_sel:[1,1] op_sel_hi:[0,1]
	v_pk_mul_f32 v[4:5], v[34:35], v[38:39] op_sel:[1,1] op_sel_hi:[0,1]
	v_pk_fma_f32 v[6:7], v[32:33], v[36:37], v[2:3] op_sel_hi:[1,0,1] neg_lo:[0,0,1]
	v_pk_fma_f32 v[8:9], v[34:35], v[38:39], v[4:5] op_sel_hi:[1,0,1] neg_lo:[0,0,1]
	v_pk_mul_f32 v[10:11], v[40:41], v[6:7]
	v_pk_mul_f32 v[12:13], v[44:45], v[6:7]
	v_pk_mul_f32 v[144:145], v[42:43], v[8:9]
	v_pk_mul_f32 v[146:147], v[46:47], v[8:9]
	v_sub_f32_e32 v10, v10, v11
	v_sub_f32_e32 v12, v12, v13
	v_sub_f32_e32 v144, v144, v145
	v_sub_f32_e32 v146, v146, v147
	v_add_f32_e32 v15, v15, v10
	v_add_f32_e32 v148, v148, v12
	v_add_f32_e32 v15, v15, v144
	v_add_f32_e32 v148, v148, v146
	ds_read_b128 v[32:35], v149 offset:352
	ds_read_b128 v[36:39], v150 offset:352
	ds_read_b128 v[40:43], v151 offset:352
	ds_read_b128 v[44:47], v151 offset:4576
	s_waitcnt lgkmcnt(8)
	v_pk_mul_f32 v[2:3], v[48:49], v[52:53] op_sel:[1,1] op_sel_hi:[0,1]
	v_pk_mul_f32 v[4:5], v[50:51], v[54:55] op_sel:[1,1] op_sel_hi:[0,1]
	v_pk_fma_f32 v[6:7], v[48:49], v[52:53], v[2:3] op_sel_hi:[1,0,1] neg_lo:[0,0,1]
	v_pk_fma_f32 v[8:9], v[50:51], v[54:55], v[4:5] op_sel_hi:[1,0,1] neg_lo:[0,0,1]
	v_pk_mul_f32 v[10:11], v[56:57], v[6:7]
	v_pk_mul_f32 v[12:13], v[60:61], v[6:7]
	v_pk_mul_f32 v[144:145], v[58:59], v[8:9]
	v_pk_mul_f32 v[146:147], v[62:63], v[8:9]
	v_sub_f32_e32 v10, v10, v11
	v_sub_f32_e32 v12, v12, v13
	v_sub_f32_e32 v144, v144, v145
	v_sub_f32_e32 v146, v146, v147
	v_add_f32_e32 v15, v15, v10
	v_add_f32_e32 v148, v148, v12
	v_add_f32_e32 v15, v15, v144
	v_add_f32_e32 v148, v148, v146
	ds_read_b128 v[48:51], v149 offset:368
	ds_read_b128 v[52:55], v150 offset:368
	ds_read_b128 v[56:59], v151 offset:368
	ds_read_b128 v[60:63], v151 offset:4592
	s_waitcnt lgkmcnt(8)
; __global__ void __launch_bounds__(512, 2) fwd_mega(Args a) {
;     ...
;             for (int n = 0; n < 64; ++n) {
;                 const float wr_ = apow[((size_t)(dg * 17 + tau) * 64 + n) * 2], wi_ = apow[((size_t)(dg * 17 + tau) * 64 + n) * 2 + 1];
;                 const float br = Bbar[(((size_t)dg * 64 + n) * 16 + p2) * 2], bi = Bbar[(((size_t)dg * 64 + n) * 16 + p2) * 2 + 1];
;                 const float xr = wr_ * br - wi_ * bi, xi = wr_ * bi + wi_ * br;
;                 acc += c_re[((size_t)dg * 16 + p) * 64 + n] * xr - c_im[((size_t)dg * 16 + p) * 64 + n] * xi;
;             }
	v_pk_mul_f32 v[2:3], v[16:17], v[20:21] op_sel:[1,1] op_sel_hi:[0,1]
	v_pk_mul_f32 v[4:5], v[18:19], v[22:23] op_sel:[1,1] op_sel_hi:[0,1]
	v_pk_fma_f32 v[6:7], v[16:17], v[20:21], v[2:3] op_sel_hi:[1,0,1] neg_lo:[0,0,1]
	v_pk_fma_f32 v[8:9], v[18:19], v[22:23], v[4:5] op_sel_hi:[1,0,1] neg_lo:[0,0,1]
	v_pk_mul_f32 v[10:11], v[24:25], v[6:7]
	v_pk_mul_f32 v[12:13], v[28:29], v[6:7]
	v_pk_mul_f32 v[144:145], v[26:27], v[8:9]
	v_pk_mul_f32 v[146:147], v[30:31], v[8:9]
	v_sub_f32_e32 v10, v10, v11
	v_sub_f32_e32 v12, v12, v13
	v_sub_f32_e32 v144, v144, v145
	v_sub_f32_e32 v146, v146, v147
	v_add_f32_e32 v15, v15, v10
	v_add_f32_e32 v148, v148, v12
	v_add_f32_e32 v15, v15, v144
	v_add_f32_e32 v148, v148, v146
	ds_read_b128 v[16:19], v149 offset:384
	ds_read_b128 v[20:23], v150 offset:384
	ds_read_b128 v[24:27], v151 offset:384
	ds_read_b128 v[28:31], v151 offset:4608
	s_waitcnt lgkmcnt(8)
	v_pk_mul_f32 v[2:3], v[32:33], v[36:37] op_sel:[1,1] op_sel_hi:[0,1]
	v_pk_mul_f32 v[4:5], v[34:35], v[38:39] op_sel:[1,1] op_sel_hi:[0,1]
	v_pk_fma_f32 v[6:7], v[32:33], v[36:37], v[2:3] op_sel_hi:[1,0,1] neg_lo:[0,0,1]
	v_pk_fma_f32 v[8:9], v[34:35], v[38:39], v[4:5] op_sel_hi:[1,0,1] neg_lo:[0,0,1]
	v_pk_mul_f32 v[10:11], v[40:41], v[6:7]
	v_pk_mul_f32 v[12:13], v[44:45], v[6:7]
	v_pk_mul_f32 v[144:145], v[42:43], v[8:9]
	v_pk_mul_f32 v[146:147], v[46:47], v[8:9]
	v_sub_f32_e32 v10, v10, v11
	v_sub_f32_e32 v12, v12, v13
	v_sub_f32_e32 v144, v144, v145
	v_sub_f32_e32 v146, v146, v147
	v_add_f32_e32 v15, v15, v10
	v_add_f32_e32 v148, v148, v12
	v_add_f32_e32 v15, v15, v144
	v_add_f32_e32 v148, v148, v146
	ds_read_b128 v[32:35], v149 offset:400
	ds_read_b128 v[36:39], v150 offset:400
	ds_read_b128 v[40:43], v151 offset:400
	ds_read_b128 v[44:47], v151 offset:4624
	s_waitcnt lgkmcnt(8)
	v_pk_mul_f32 v[2:3], v[48:49], v[52:53] op_sel:[1,1] op_sel_hi:[0,1]
	v_pk_mul_f32 v[4:5], v[50:51], v[54:55] op_sel:[1,1] op_sel_hi:[0,1]
	v_pk_fma_f32 v[6:7], v[48:49], v[52:53], v[2:3] op_sel_hi:[1,0,1] neg_lo:[0,0,1]
	v_pk_fma_f32 v[8:9], v[50:51], v[54:55], v[4:5] op_sel_hi:[1,0,1] neg_lo:[0,0,1]
	v_pk_mul_f32 v[10:11], v[56:57], v[6:7]
	v_pk_mul_f32 v[12:13], v[60:61], v[6:7]
	v_pk_mul_f32 v[144:145], v[58:59], v[8:9]
	v_pk_mul_f32 v[146:147], v[62:63], v[8:9]
	v_sub_f32_e32 v10, v10, v11
	v_sub_f32_e32 v12, v12, v13
	v_sub_f32_e32 v144, v144, v145
	v_sub_f32_e32 v146, v146, v147
	v_add_f32_e32 v15, v15, v10
	v_add_f32_e32 v148, v148, v12
	v_add_f32_e32 v15, v15, v144
	v_add_f32_e32 v148, v148, v146
	ds_read_b128 v[48:51], v149 offset:416
	ds_read_b128 v[52:55], v150 offset:416
	ds_read_b128 v[56:59], v151 offset:416
	ds_read_b128 v[60:63], v151 offset:4640
	s_waitcnt lgkmcnt(8)
	v_pk_mul_f32 v[2:3], v[16:17], v[20:21] op_sel:[1,1] op_sel_hi:[0,1]
	v_pk_mul_f32 v[4:5], v[18:19], v[22:23] op_sel:[1,1] op_sel_hi:[0,1]
	v_pk_fma_f32 v[6:7], v[16:17], v[20:21], v[2:3] op_sel_hi:[1,0,1] neg_lo:[0,0,1]
	v_pk_fma_f32 v[8:9], v[18:19], v[22:23], v[4:5] op_sel_hi:[1,0,1] neg_lo:[0,0,1]
	v_pk_mul_f32 v[10:11], v[24:25], v[6:7]
	v_pk_mul_f32 v[12:13], v[28:29], v[6:7]
	v_pk_mul_f32 v[144:145], v[26:27], v[8:9]
	v_pk_mul_f32 v[146:147], v[30:31], v[8:9]
	v_sub_f32_e32 v10, v10, v11
	v_sub_f32_e32 v12, v12, v13
	v_sub_f32_e32 v144, v144, v145
	v_sub_f32_e32 v146, v146, v147
	v_add_f32_e32 v15, v15, v10
	v_add_f32_e32 v148, v148, v12
	v_add_f32_e32 v15, v15, v144
	v_add_f32_e32 v148, v148, v146
	ds_read_b128 v[16:19], v149 offset:432
	ds_read_b128 v[20:23], v150 offset:432
	ds_read_b128 v[24:27], v151 offset:432
	ds_read_b128 v[28:31], v151 offset:4656
	s_waitcnt lgkmcnt(8)
	v_pk_mul_f32 v[2:3], v[32:33], v[36:37] op_sel:[1,1] op_sel_hi:[0,1]
	v_pk_mul_f32 v[4:5], v[34:35], v[38:39] op_sel:[1,1] op_sel_hi:[0,1]
	v_pk_fma_f32 v[6:7], v[32:33], v[36:37], v[2:3] op_sel_hi:[1,0,1] neg_lo:[0,0,1]
	v_pk_fma_f32 v[8:9], v[34:35], v[38:39], v[4:5] op_sel_hi:[1,0,1] neg_lo:[0,0,1]
	v_pk_mul_f32 v[10:11], v[40:41], v[6:7]
	v_pk_mul_f32 v[12:13], v[44:45], v[6:7]
	v_pk_mul_f32 v[144:145], v[42:43], v[8:9]
	v_pk_mul_f32 v[146:147], v[46:47], v[8:9]
	v_sub_f32_e32 v10, v10, v11
	v_sub_f32_e32 v12, v12, v13
	v_sub_f32_e32 v144, v144, v145
	v_sub_f32_e32 v146, v146, v147
	v_add_f32_e32 v15, v15, v10
	v_add_f32_e32 v148, v148, v12
	v_add_f32_e32 v15, v15, v144
	v_add_f32_e32 v148, v148, v146
	ds_read_b128 v[32:35], v149 offset:448
	ds_read_b128 v[36:39], v150 offset:448
	ds_read_b128 v[40:43], v151 offset:448
	ds_read_b128 v[44:47], v151 offset:4672
	s_waitcnt lgkmcnt(8)
	v_pk_mul_f32 v[2:3], v[48:49], v[52:53] op_sel:[1,1] op_sel_hi:[0,1]
	v_pk_mul_f32 v[4:5], v[50:51], v[54:55] op_sel:[1,1] op_sel_hi:[0,1]
	v_pk_fma_f32 v[6:7], v[48:49], v[52:53], v[2:3] op_sel_hi:[1,0,1] neg_lo:[0,0,1]
	v_pk_fma_f32 v[8:9], v[50:51], v[54:55], v[4:5] op_sel_hi:[1,0,1] neg_lo:[0,0,1]
	v_pk_mul_f32 v[10:11], v[56:57], v[6:7]
	v_pk_mul_f32 v[12:13], v[60:61], v[6:7]
	v_pk_mul_f32 v[144:145], v[58:59], v[8:9]
	v_pk_mul_f32 v[146:147], v[62:63], v[8:9]
	v_sub_f32_e32 v10, v10, v11
	v_sub_f32_e32 v12, v12, v13
	v_sub_f32_e32 v144, v144, v145
	v_sub_f32_e32 v146, v146, v147
	v_add_f32_e32 v15, v15, v10
	v_add_f32_e32 v148, v148, v12
	v_add_f32_e32 v15, v15, v144
	v_add_f32_e32 v148, v148, v146
	ds_read_b128 v[48:51], v149 offset:464
	ds_read_b128 v[52:55], v150 offset:464
	ds_read_b128 v[56:59], v151 offset:464
	ds_read_b128 v[60:63], v151 offset:4688
	s_waitcnt lgkmcnt(8)
; __global__ void __launch_bounds__(512, 2) fwd_mega(Args a) {
;     ...
;             for (int n = 0; n < 64; ++n) {
;                 const float wr_ = apow[((size_t)(dg * 17 + tau) * 64 + n) * 2], wi_ = apow[((size_t)(dg * 17 + tau) * 64 + n) * 2 + 1];
;                 const float br = Bbar[(((size_t)dg * 64 + n) * 16 + p2) * 2], bi = Bbar[(((size_t)dg * 64 + n) * 16 + p2) * 2 + 1];
;                 const float xr = wr_ * br - wi_ * bi, xi = wr_ * bi + wi_ * br;
;                 acc += c_re[((size_t)dg * 16 + p) * 64 + n] * xr - c_im[((size_t)dg * 16 + p) * 64 + n] * xi;
;             }
;             Kt[idx] = acc;
;     ...
;         for (int idx = gtid; idx < 32 * 256 * 32; idx += NTH) {
;             const int k8 = idx & 31, o = (idx >> 5) & 255, g = idx >> 13, j = k8 >> 1, p0 = (k8 & 1) * 8;
;             const int dir = o >> 7, ri = (o >> 6) & 1, n = o & 63, dg = dir * 32 + g, e = dir ? j : 15 - j;
;             const float wr_ = apow[((size_t)(dg * 17 + e) * 64 + n) * 2], wi_ = apow[((size_t)(dg * 17 + e) * 64 + n) * 2 + 1];
	v_pk_mul_f32 v[2:3], v[16:17], v[20:21] op_sel:[1,1] op_sel_hi:[0,1]
	v_pk_mul_f32 v[4:5], v[18:19], v[22:23] op_sel:[1,1] op_sel_hi:[0,1]
	v_pk_fma_f32 v[6:7], v[16:17], v[20:21], v[2:3] op_sel_hi:[1,0,1] neg_lo:[0,0,1]
	v_pk_fma_f32 v[8:9], v[18:19], v[22:23], v[4:5] op_sel_hi:[1,0,1] neg_lo:[0,0,1]
	v_pk_mul_f32 v[10:11], v[24:25], v[6:7]
	v_pk_mul_f32 v[12:13], v[28:29], v[6:7]
	v_pk_mul_f32 v[144:145], v[26:27], v[8:9]
	v_pk_mul_f32 v[146:147], v[30:31], v[8:9]
	v_sub_f32_e32 v10, v10, v11
	v_sub_f32_e32 v12, v12, v13
	v_sub_f32_e32 v144, v144, v145
	v_sub_f32_e32 v146, v146, v147
	v_add_f32_e32 v15, v15, v10
	v_add_f32_e32 v148, v148, v12
	v_add_f32_e32 v15, v15, v144
	v_add_f32_e32 v148, v148, v146
	ds_read_b128 v[16:19], v149 offset:480
	ds_read_b128 v[20:23], v150 offset:480
	ds_read_b128 v[24:27], v151 offset:480
	ds_read_b128 v[28:31], v151 offset:4704
	s_waitcnt lgkmcnt(8)
	v_pk_mul_f32 v[2:3], v[32:33], v[36:37] op_sel:[1,1] op_sel_hi:[0,1]
	v_pk_mul_f32 v[4:5], v[34:35], v[38:39] op_sel:[1,1] op_sel_hi:[0,1]
	v_pk_fma_f32 v[6:7], v[32:33], v[36:37], v[2:3] op_sel_hi:[1,0,1] neg_lo:[0,0,1]
	v_pk_fma_f32 v[8:9], v[34:35], v[38:39], v[4:5] op_sel_hi:[1,0,1] neg_lo:[0,0,1]
	v_pk_mul_f32 v[10:11], v[40:41], v[6:7]
	v_pk_mul_f32 v[12:13], v[44:45], v[6:7]
	v_pk_mul_f32 v[144:145], v[42:43], v[8:9]
	v_pk_mul_f32 v[146:147], v[46:47], v[8:9]
	v_sub_f32_e32 v10, v10, v11
	v_sub_f32_e32 v12, v12, v13
	v_sub_f32_e32 v144, v144, v145
	v_sub_f32_e32 v146, v146, v147
	v_add_f32_e32 v15, v15, v10
	v_add_f32_e32 v148, v148, v12
	v_add_f32_e32 v15, v15, v144
	v_add_f32_e32 v148, v148, v146
	ds_read_b128 v[32:35], v149 offset:496
	ds_read_b128 v[36:39], v150 offset:496
	ds_read_b128 v[40:43], v151 offset:496
	ds_read_b128 v[44:47], v151 offset:4720
	s_waitcnt lgkmcnt(8)
	v_pk_mul_f32 v[2:3], v[48:49], v[52:53] op_sel:[1,1] op_sel_hi:[0,1]
	v_pk_mul_f32 v[4:5], v[50:51], v[54:55] op_sel:[1,1] op_sel_hi:[0,1]
	v_pk_fma_f32 v[6:7], v[48:49], v[52:53], v[2:3] op_sel_hi:[1,0,1] neg_lo:[0,0,1]
	v_pk_fma_f32 v[8:9], v[50:51], v[54:55], v[4:5] op_sel_hi:[1,0,1] neg_lo:[0,0,1]
	v_pk_mul_f32 v[10:11], v[56:57], v[6:7]
	v_pk_mul_f32 v[12:13], v[60:61], v[6:7]
	v_pk_mul_f32 v[144:145], v[58:59], v[8:9]
	v_pk_mul_f32 v[146:147], v[62:63], v[8:9]
	v_sub_f32_e32 v10, v10, v11
	v_sub_f32_e32 v12, v12, v13
	v_sub_f32_e32 v144, v144, v145
	v_sub_f32_e32 v146, v146, v147
	v_add_f32_e32 v15, v15, v10
	v_add_f32_e32 v148, v148, v12
	v_add_f32_e32 v15, v15, v144
	v_add_f32_e32 v148, v148, v146
	s_waitcnt lgkmcnt(4)
	v_pk_mul_f32 v[2:3], v[16:17], v[20:21] op_sel:[1,1] op_sel_hi:[0,1]
	v_pk_mul_f32 v[4:5], v[18:19], v[22:23] op_sel:[1,1] op_sel_hi:[0,1]
	v_pk_fma_f32 v[6:7], v[16:17], v[20:21], v[2:3] op_sel_hi:[1,0,1] neg_lo:[0,0,1]
	v_pk_fma_f32 v[8:9], v[18:19], v[22:23], v[4:5] op_sel_hi:[1,0,1] neg_lo:[0,0,1]
	v_pk_mul_f32 v[10:11], v[24:25], v[6:7]
	v_pk_mul_f32 v[12:13], v[28:29], v[6:7]
	v_pk_mul_f32 v[144:145], v[26:27], v[8:9]
	v_pk_mul_f32 v[146:147], v[30:31], v[8:9]
	v_sub_f32_e32 v10, v10, v11
	v_sub_f32_e32 v12, v12, v13
	v_sub_f32_e32 v144, v144, v145
	v_sub_f32_e32 v146, v146, v147
	v_add_f32_e32 v15, v15, v10
	v_add_f32_e32 v148, v148, v12
	v_add_f32_e32 v15, v15, v144
	v_add_f32_e32 v148, v148, v146
	s_waitcnt lgkmcnt(0)
	v_pk_mul_f32 v[2:3], v[32:33], v[36:37] op_sel:[1,1] op_sel_hi:[0,1]
	v_pk_mul_f32 v[4:5], v[34:35], v[38:39] op_sel:[1,1] op_sel_hi:[0,1]
	v_pk_fma_f32 v[6:7], v[32:33], v[36:37], v[2:3] op_sel_hi:[1,0,1] neg_lo:[0,0,1]
	v_pk_fma_f32 v[8:9], v[34:35], v[38:39], v[4:5] op_sel_hi:[1,0,1] neg_lo:[0,0,1]
	v_pk_mul_f32 v[10:11], v[40:41], v[6:7]
	v_pk_mul_f32 v[12:13], v[44:45], v[6:7]
	v_pk_mul_f32 v[144:145], v[42:43], v[8:9]
	v_pk_mul_f32 v[146:147], v[46:47], v[8:9]
	v_sub_f32_e32 v10, v10, v11
	v_sub_f32_e32 v12, v12, v13
	v_sub_f32_e32 v144, v144, v145
	v_sub_f32_e32 v146, v146, v147
	v_add_f32_e32 v15, v15, v10
	v_add_f32_e32 v148, v148, v12
	v_add_f32_e32 v15, v15, v144
	v_add_f32_e32 v148, v148, v146
	s_lshl_b32 s10, s4, 14
	s_lshl_b32 s17, s5, 12
	s_add_i32 s10, s10, s17
	s_lshr_b32 s17, s79, 7
	s_lshl_b32 s17, s17, 10
	s_add_i32 s10, s10, s17
	s_add_u32 s40, s38, s10
	s_addc_u32 s41, s39, 0
	v_bfe_u32 v2, v0, 4, 3
	v_and_b32_e32 v3, 15, v0
	v_lshlrev_b32_e32 v2, 6, v2
	v_lshl_add_u32 v2, v3, 2, v2
	global_store_dword v2, v15, s[40:41]
	global_store_dword v2, v148, s[40:41] offset:512
	s_add_u32 s38, s30, 0x2500000
	v_and_b32_e32 v7, 31, v1
	s_addc_u32 s39, s31, 0
	v_mov_b32_e32 v3, 0
	v_lshlrev_b32_e32 v2, 4, v7
	s_add_u32 s4, s30, 0x2600000
	v_bfe_u32 v1, v1, 1, 4
	v_lshl_add_u64 v[4:5], s[30:31], 0, v[2:3]
	s_mov_b64 s[10:11], 0x1500000
	v_lshlrev_b32_e32 v6, 3, v14
	s_addc_u32 s5, s31, 0
	v_xor_b32_e32 v8, 15, v1
	v_lshlrev_b32_e32 v0, 3, v7
	v_lshl_add_u64 v[4:5], v[4:5], 0, s[10:11]
	s_lshl_b32 s10, s18, 12
	s_mov_b64 s[40:41], 0
	s_movk_i32 s11, 0x80
	s_mov_b32 s17, 0x3ffff
	v_mov_b32_e32 v9, v6
	v_mov_b32_e32 v10, v14
